# v9: + NA key-norm trims (v_add_f32_dpp, rsq denormal guard removed)
# baseline (speedup 1.0000x reference)
; #define LAS __attribute__((address_space(3)))
; __device__ __forceinline__ unsigned pk_bf16(float lo, float hi) { unsigned r; asm volatile("v_cvt_pk_bf16_f32 %0, %1, %2" : "=v"(r) : "v"(lo), "v"(hi)); return r; }
; __device__ __forceinline__ float bflo(unsigned w) { return __uint_as_float(w << 16); }
; __device__ __forceinline__ float bfhi(unsigned w) { return __uint_as_float(w & 0xffff0000u); }
; __device__ __forceinline__ float shx(float v, int m, int lane) { return __int_as_float(__builtin_amdgcn_ds_bpermute((lane ^ m) << 2, __float_as_int(v))); }
; __device__ __forceinline__ u32x4 norm_krow(u32x4 w, int lane) {
;     float v[8]; v[0] = bflo(w.x); v[1] = bfhi(w.x); v[2] = bflo(w.y); v[3] = bfhi(w.y); v[4] = bflo(w.z); v[5] = bfhi(w.z); v[6] = bflo(w.w); v[7] = bfhi(w.w);
;     float ss = 0.f;
; #pragma unroll
;     for (int e = 0; e < 8; ++e) ss += v[e] * v[e];
;     ss += shx(ss, 1, lane); ss += shx(ss, 2, lane); ss += shx(ss, 4, lane);
;     const float rk = rsqrtf(ss * (1.0f / 64.0f) + 1e-6f);
;     u32x4 o; o.x = pk_bf16(v[0] * rk, v[1] * rk); o.y = pk_bf16(v[2] * rk, v[3] * rk); o.z = pk_bf16(v[4] * rk, v[5] * rk); o.w = pk_bf16(v[6] * rk, v[7] * rk); return o;
; }
; __device__ __forceinline__ void na_item(int wv, const Params& p, int l, int it, LAS unsigned char* lds) {
;     ...
; #pragma unroll
;             for (int i = 0; i < 5; ++i) { const int e = tid + i * 512, key = e >> 3, seg = e & 7; *(LAS u32x4*)(lds + NB_KLOC + key * 144 + seg * 16) = norm_krow(kl[i], lane); }
; #pragma unroll
;             for (int i = 0; i < 5; ++i) { const int e = tid + i * 512, d = e / 40, seg = e % 40; *(LAS u32x4*)(lds + NB_VLOC + d * 656 + seg * 16) = vl[i]; }
.LBB0_746:
	s_or_b64 exec, exec, s[50:51]
	s_and_b64 vcc, exec, s[14:15]
	s_cbranch_vccnz .LBB0_748
	s_waitcnt vmcnt(4)
	v_lshlrev_b32_e32 v2, 16, v16
	v_and_b32_e32 v3, 0xffff0000, v16
	v_pk_mul_f32 v[84:85], v[2:3], v[2:3]
	v_and_b32_e32 v86, 0xffff0000, v17
	v_lshlrev_b32_e32 v87, 16, v17
	v_pk_mul_f32 v[88:89], v[86:87], v[86:87]
	v_add_f32_e32 v0, v84, v85
	v_and_b32_e32 v90, 0xffff0000, v18
	v_lshlrev_b32_e32 v91, 16, v18
	v_add_f32_e32 v0, v89, v0
	v_pk_mul_f32 v[92:93], v[90:91], v[90:91]
	v_add_f32_e32 v0, v88, v0
	v_and_b32_e32 v94, 0xffff0000, v19
	v_lshlrev_b32_e32 v95, 16, v19
	v_add_f32_e32 v0, v93, v0
	v_pk_mul_f32 v[96:97], v[94:95], v[94:95]
	v_add_f32_e32 v0, v92, v0
	v_add_f32_e32 v0, v97, v0
	v_add_f32_e32 v0, v96, v0
	s_nop 1
	v_add_f32_dpp v0, v0, v0 quad_perm:[1,0,3,2] row_mask:0xf bank_mask:0xf
	s_nop 1
	v_add_f32_dpp v0, v0, v0 quad_perm:[2,3,0,1] row_mask:0xf bank_mask:0xf
	s_nop 1
	v_add_f32_dpp v0, v0, v0 row_half_mirror row_mask:0xf bank_mask:0xf
	v_fmamk_f32 v0, v0, 0x3c800000, v197
	v_rsq_f32_e32 v0, v0
	s_nop 0
	v_mul_f32_e32 v2, v0, v2
	v_mul_f32_e32 v3, v0, v3
	v_cvt_pk_bf16_f32 v84, v2, v3
	v_mul_f32_e32 v2, v0, v87
	v_mul_f32_e32 v3, v0, v86
	v_cvt_pk_bf16_f32 v85, v2, v3
	v_mul_f32_e32 v2, v0, v91
	v_mul_f32_e32 v3, v0, v90
	v_cvt_pk_bf16_f32 v86, v2, v3
	v_mul_f32_e32 v2, v0, v95
	v_mul_f32_e32 v0, v0, v94
	v_cvt_pk_bf16_f32 v87, v2, v0
	v_add_u32_e32 v0, v143, v160
	v_lshlrev_b32_e32 v2, 16, v12
	v_and_b32_e32 v3, 0xffff0000, v12
	ds_write_b128 v0, v[84:87]
	v_pk_mul_f32 v[84:85], v[2:3], v[2:3]
	v_and_b32_e32 v86, 0xffff0000, v13
	v_lshlrev_b32_e32 v87, 16, v13
	v_pk_mul_f32 v[88:89], v[86:87], v[86:87]
	v_add_f32_e32 v0, v84, v85
	v_and_b32_e32 v90, 0xffff0000, v14
	v_lshlrev_b32_e32 v91, 16, v14
	v_add_f32_e32 v0, v89, v0
	v_pk_mul_f32 v[92:93], v[90:91], v[90:91]
	v_add_f32_e32 v0, v88, v0
	v_and_b32_e32 v94, 0xffff0000, v15
	v_lshlrev_b32_e32 v95, 16, v15
	v_add_f32_e32 v0, v93, v0
	v_pk_mul_f32 v[96:97], v[94:95], v[94:95]
	v_add_f32_e32 v0, v92, v0
	v_add_f32_e32 v0, v97, v0
	v_add_f32_e32 v0, v96, v0
	s_nop 1
	v_add_f32_dpp v0, v0, v0 quad_perm:[1,0,3,2] row_mask:0xf bank_mask:0xf
	s_nop 1
	v_add_f32_dpp v0, v0, v0 quad_perm:[2,3,0,1] row_mask:0xf bank_mask:0xf
	s_nop 1
	v_add_f32_dpp v0, v0, v0 row_half_mirror row_mask:0xf bank_mask:0xf
	v_fmamk_f32 v0, v0, 0x3c800000, v197
	v_rsq_f32_e32 v0, v0
	s_nop 0
	v_mul_f32_e32 v2, v0, v2
	v_mul_f32_e32 v3, v0, v3
	v_cvt_pk_bf16_f32 v84, v2, v3
	v_mul_f32_e32 v2, v0, v87
	v_mul_f32_e32 v3, v0, v86
	v_cvt_pk_bf16_f32 v85, v2, v3
	v_mul_f32_e32 v2, v0, v91
	v_mul_f32_e32 v3, v0, v90
	v_cvt_pk_bf16_f32 v86, v2, v3
	v_mul_f32_e32 v2, v0, v95
	v_mul_f32_e32 v0, v0, v94
	v_cvt_pk_bf16_f32 v87, v2, v0
	v_add_u32_e32 v0, v143, v161
	v_lshlrev_b32_e32 v2, 16, v20
	v_and_b32_e32 v3, 0xffff0000, v20
	ds_write_b128 v0, v[84:87]
	v_pk_mul_f32 v[84:85], v[2:3], v[2:3]
	v_and_b32_e32 v86, 0xffff0000, v21
	v_lshlrev_b32_e32 v87, 16, v21
	v_pk_mul_f32 v[88:89], v[86:87], v[86:87]
	v_add_f32_e32 v0, v84, v85
	v_and_b32_e32 v90, 0xffff0000, v22
	v_lshlrev_b32_e32 v91, 16, v22
	v_add_f32_e32 v0, v89, v0
	v_pk_mul_f32 v[92:93], v[90:91], v[90:91]
	v_add_f32_e32 v0, v88, v0
	v_and_b32_e32 v94, 0xffff0000, v23
	v_lshlrev_b32_e32 v95, 16, v23
	v_add_f32_e32 v0, v93, v0
	v_pk_mul_f32 v[96:97], v[94:95], v[94:95]
	v_add_f32_e32 v0, v92, v0
	v_add_f32_e32 v0, v97, v0
	v_add_f32_e32 v0, v96, v0
	s_nop 1
	v_add_f32_dpp v0, v0, v0 quad_perm:[1,0,3,2] row_mask:0xf bank_mask:0xf
	s_nop 1
	v_add_f32_dpp v0, v0, v0 quad_perm:[2,3,0,1] row_mask:0xf bank_mask:0xf
	s_nop 1
	v_add_f32_dpp v0, v0, v0 row_half_mirror row_mask:0xf bank_mask:0xf
	v_fmamk_f32 v0, v0, 0x3c800000, v197
	v_rsq_f32_e32 v0, v0
	s_nop 0
	v_mul_f32_e32 v2, v0, v2
	v_mul_f32_e32 v3, v0, v3
	v_cvt_pk_bf16_f32 v84, v2, v3
	v_mul_f32_e32 v2, v0, v87
	v_mul_f32_e32 v3, v0, v86
	v_cvt_pk_bf16_f32 v85, v2, v3
	v_mul_f32_e32 v2, v0, v91
	v_mul_f32_e32 v3, v0, v90
	v_cvt_pk_bf16_f32 v86, v2, v3
	v_mul_f32_e32 v2, v0, v95
	v_mul_f32_e32 v0, v0, v94
	v_cvt_pk_bf16_f32 v87, v2, v0
	v_lshlrev_b32_e32 v2, 16, v24
	v_and_b32_e32 v3, 0xffff0000, v24
	ds_write_b128 v176, v[84:87]
	v_pk_mul_f32 v[84:85], v[2:3], v[2:3]
	v_and_b32_e32 v86, 0xffff0000, v25
	v_lshlrev_b32_e32 v87, 16, v25
	v_pk_mul_f32 v[88:89], v[86:87], v[86:87]
	v_add_f32_e32 v0, v84, v85
	v_and_b32_e32 v90, 0xffff0000, v26
	v_lshlrev_b32_e32 v91, 16, v26
	v_add_f32_e32 v0, v89, v0
	v_pk_mul_f32 v[92:93], v[90:91], v[90:91]
	v_add_f32_e32 v0, v88, v0
	v_and_b32_e32 v94, 0xffff0000, v27
	v_lshlrev_b32_e32 v95, 16, v27
	v_add_f32_e32 v0, v93, v0
	v_pk_mul_f32 v[96:97], v[94:95], v[94:95]
	v_add_f32_e32 v0, v92, v0
	v_add_f32_e32 v0, v97, v0
	v_add_f32_e32 v0, v96, v0
	s_nop 1
	v_add_f32_dpp v0, v0, v0 quad_perm:[1,0,3,2] row_mask:0xf bank_mask:0xf
	s_nop 1
	v_add_f32_dpp v0, v0, v0 quad_perm:[2,3,0,1] row_mask:0xf bank_mask:0xf
	s_nop 1
	v_add_f32_dpp v0, v0, v0 row_half_mirror row_mask:0xf bank_mask:0xf
	v_fmamk_f32 v0, v0, 0x3c800000, v197
	v_rsq_f32_e32 v0, v0
	s_nop 0
	v_mul_f32_e32 v2, v0, v2
	v_mul_f32_e32 v3, v0, v3
	v_cvt_pk_bf16_f32 v84, v2, v3
	v_mul_f32_e32 v2, v0, v87
	v_mul_f32_e32 v3, v0, v86
	v_cvt_pk_bf16_f32 v85, v2, v3
	v_mul_f32_e32 v2, v0, v91
	v_mul_f32_e32 v3, v0, v90
	v_cvt_pk_bf16_f32 v86, v2, v3
	v_mul_f32_e32 v2, v0, v95
	v_mul_f32_e32 v0, v0, v94
	v_cvt_pk_bf16_f32 v87, v2, v0
	v_lshlrev_b32_e32 v2, 16, v28
	v_and_b32_e32 v3, 0xffff0000, v28
	ds_write_b128 v177, v[84:87]
	v_pk_mul_f32 v[84:85], v[2:3], v[2:3]
	v_and_b32_e32 v86, 0xffff0000, v29
	v_lshlrev_b32_e32 v87, 16, v29
	v_pk_mul_f32 v[88:89], v[86:87], v[86:87]
	v_add_f32_e32 v0, v84, v85
	v_and_b32_e32 v90, 0xffff0000, v30
	v_lshlrev_b32_e32 v91, 16, v30
	v_add_f32_e32 v0, v89, v0
	v_pk_mul_f32 v[92:93], v[90:91], v[90:91]
	v_add_f32_e32 v0, v88, v0
	v_and_b32_e32 v94, 0xffff0000, v31
	v_lshlrev_b32_e32 v95, 16, v31
	v_add_f32_e32 v0, v93, v0
	v_pk_mul_f32 v[96:97], v[94:95], v[94:95]
	v_add_f32_e32 v0, v92, v0
	v_add_f32_e32 v0, v97, v0
	v_add_f32_e32 v0, v96, v0
	s_nop 1
	v_add_f32_dpp v0, v0, v0 quad_perm:[1,0,3,2] row_mask:0xf bank_mask:0xf
	s_nop 1
	v_add_f32_dpp v0, v0, v0 quad_perm:[2,3,0,1] row_mask:0xf bank_mask:0xf
	s_nop 1
	v_add_f32_dpp v0, v0, v0 row_half_mirror row_mask:0xf bank_mask:0xf
	v_fmamk_f32 v0, v0, 0x3c800000, v197
	v_rsq_f32_e32 v0, v0
	s_nop 0
	v_mul_f32_e32 v2, v0, v2
	v_mul_f32_e32 v3, v0, v3
	v_cvt_pk_bf16_f32 v84, v2, v3
	v_mul_f32_e32 v2, v0, v87
	v_mul_f32_e32 v3, v0, v86
	v_cvt_pk_bf16_f32 v85, v2, v3
	v_mul_f32_e32 v2, v0, v91
	v_mul_f32_e32 v3, v0, v90
	v_cvt_pk_bf16_f32 v86, v2, v3
	v_mul_f32_e32 v2, v0, v95
	v_mul_f32_e32 v0, v0, v94
	v_cvt_pk_bf16_f32 v87, v2, v0
	ds_write_b128 v178, v[84:87]
	s_waitcnt vmcnt(8)
	ds_write_b128 v179, v[32:35] offset:46080
	s_waitcnt vmcnt(7)
	ds_write_b128 v180, v[36:39] offset:46080
	s_waitcnt vmcnt(6)
	ds_write_b128 v181, v[40:43] offset:46080
	s_waitcnt vmcnt(5)
	ds_write_b128 v182, v[44:47] offset:46080
	s_waitcnt vmcnt(4)
	ds_write_b128 v183, v[48:51] offset:46080
